# P7 start stagger in 8 groups (bi&7) x s_sleep 84
# baseline (speedup 1.0000x reference)
.Lp7_stag_loop:
	s_cmp_eq_u32 s6, 0
	s_cbranch_scc1 .Lp7_nostag
	s_sleep 84
	s_add_i32 s6, s6, -1
	s_branch .Lp7_stag_loop
